# conv epilogue: mt pairs merged into dwordx4 stores via permlane16_swap (8 instead of 16 store instructions per wave)
# speedup vs baseline: 1.0190x; 1.0076x over previous
; #define LAS __attribute__((address_space(3)))
; #define GAS __attribute__((address_space(1)))
; #define LAUNDER_V(x) asm volatile("" : "+v"(x))
; __device__ __forceinline__ unsigned pk2(float lo, float hi) { const f32x2_t f = {lo, hi}; const bf16x2_t b = __builtin_convertvector(f, bf16x2_t); return __builtin_bit_cast(unsigned, b); }
; __device__ __forceinline__ float lo16(unsigned v) { return __uint_as_float(v << 16); }
; __device__ __forceinline__ float hi16(unsigned v) { return __uint_as_float(v & 0xffff0000u); }
; __device__ __forceinline__ void conv_item(const Params& P, int slice, int item, LAS unsigned char* lds) {
;     ...
;       const int gc = 1024 * (order + 1) + c; const u16* grow = hyT + (size_t)gc * TS;
;       const float w0 = wsh[gc], w1 = wsh[3072 + gc], w2 = wsh[6144 + gc], bb = bsh[gc], skip = P.in[I_FSK][order * 1024 + c];
;       GAS u16* zt = (GAS u16*)(ws + O_ZT) + (size_t)c * TS;
;       int te = threadIdx.x; LAUNDER_V(te); const int l16 = te & 15, kc = (te >> 4) & 3;
; #pragma unroll
;       for (int nt = 0; nt < 2; ++nt) {
;         Sc4Raw gr[2][4];
; #pragma unroll
;         for (int hh = 0; hh < 2; ++hh) {
;           const int n = 32 * (2 * wn + nt) + 16 * hh + l16, bk = n >> nbsh, bs = n & (nb - 1), Bo = bs * nblk + bk;
; #pragma unroll
;           for (int mt = 0; mt < 4; ++mt) gr[hh][mt] = sc4_load(grow, Bo * 128 + 64 * wm + 16 * mt + 4 * kc);
;         }
;         __builtin_amdgcn_sched_barrier(0);
; #pragma unroll
;         for (int hh = 0; hh < 2; ++hh) {
;           const int n = 32 * (2 * wn + nt) + 16 * hh + l16, bk = n >> nbsh, bs = n & (nb - 1), Bo = bs * nblk + bk;
; #pragma unroll
;           for (int mt = 0; mt < 4; ++mt) {
;             const int s0 = 64 * wm + 16 * mt + 4 * kc, tok = Bo * 128 + s0;
;             LAS u32x2* zp = (LAS u32x2*)(Zs + Bo * ZBLK + bs * 32 + 2 * s0);
;             const u32x2 zv = *zp; const f32x4 gt = sc4_apply(gr[hh][mt], tok, L, w0, w1, w2, bb);
;             const f32x4 av = acc[mt][2 * nt + hh];
;             const float y0 = gt[0] * (av[0] + skip * lo16(zv.x)), y1 = gt[1] * (av[1] + skip * hi16(zv.x));
;             const float y2 = gt[2] * (av[2] + skip * lo16(zv.y)), y3 = gt[3] * (av[3] + skip * hi16(zv.y));
;             u32x2 o; o.x = pk2(y0, y1); o.y = pk2(y2, y3);
;             if (order == 0) *zp = o; else *(GAS u32x2*)(zt + (unsigned)tok) = o;
.LBB0_459:
	s_add_i32 s8, s6, 0x400
	s_ashr_i32 s9, s8, 31
	s_lshl_b64 s[0:1], s[8:9], 15
	s_add_u32 s0, s19, s0
	s_addc_u32 s1, s20, s1
	s_lshl_b64 s[8:9], s[8:9], 2
	s_add_u32 s16, s52, s8
	s_addc_u32 s17, s53, s9
	s_add_u32 s8, s54, s8
	v_readlane_b32 s68, v253, 56
	s_addc_u32 s9, s55, s9
	s_lshl_b64 s[6:7], s[6:7], 2
	v_readlane_b32 s72, v253, 60
	v_readlane_b32 s73, v253, 61
	s_add_u32 s6, s72, s6
	s_addc_u32 s7, s73, s7
	s_waitcnt vmcnt(4)
	v_mov_b32_e32 v1, v215
	global_load_dword v7, v81, s[16:17]
	global_load_dword v6, v220, s[16:17]
	global_load_dword v0, v221, s[16:17]
	global_load_dword v2, v81, s[8:9]
	global_load_dword v4, v81, s[6:7]
	s_waitcnt lgkmcnt(2)
	v_mov_b32_e32 v29, v81
	s_waitcnt vmcnt(6)
	v_and_b32_e32 v3, s56, v1
	s_waitcnt lgkmcnt(1)
	v_and_or_b32 v63, v1, 15, s23
	v_lshlrev_b32_e32 v62, s86, v3
	s_waitcnt vmcnt(5)
	v_lshrrev_b32_e32 v5, 2, v1
	v_ashrrev_i32_e32 v1, s94, v63
	v_add_u32_e32 v1, v1, v62
	v_and_or_b32 v25, v5, 12, s18
	s_waitcnt lgkmcnt(0)
	v_lshlrev_b32_e32 v72, 7, v1
	v_or_b32_e32 v80, v25, v72
	v_min_i32_e32 v24, 0x3ffb, v80
	v_add_u32_e32 v28, 4, v24
	v_lshl_add_u64 v[28:29], v[28:29], 1, s[0:1]
	v_or_b32_e32 v24, 16, v80
	global_load_ushort v91, v[28:29], off
	v_max_i32_e32 v29, 1, v24
	v_min_i32_e32 v24, 0x3ffb, v24
	v_add_u32_e32 v28, 4, v24
	v_lshlrev_b32_e32 v24, 1, v29
	v_mov_b32_e32 v29, v81
	global_load_ushort v89, v24, s[0:1] offset:-2
	v_lshl_add_u64 v[28:29], v[28:29], 1, s[0:1]
	v_or_b32_e32 v24, 32, v80
	global_load_ushort v90, v[28:29], off
	v_max_i32_e32 v29, 1, v24
	v_min_i32_e32 v24, 0x3ffb, v24
	v_add_u32_e32 v28, 4, v24
	v_lshlrev_b32_e32 v24, 1, v29
	v_lshl_add_u64 v[26:27], v[80:81], 1, s[0:1]
	global_load_ushort v83, v24, s[0:1] offset:-2
	v_or_b32_e32 v24, 48, v80
	global_load_dwordx2 v[60:61], v[26:27], off
	global_load_dwordx2 v[56:57], v[26:27], off offset:32
	global_load_dwordx2 v[38:39], v[26:27], off offset:64
	global_load_dwordx2 v[36:37], v[26:27], off offset:96
	v_max_i32_e32 v27, 1, v24
	v_min_i32_e32 v24, 0x3ffb, v24
	v_add_u32_e32 v26, 4, v24
	v_lshlrev_b32_e32 v24, 1, v27
	global_load_ushort v79, v24, s[0:1] offset:-2
	v_or_b32_e32 v24, 16, v63
	v_ashrrev_i32_e32 v24, s94, v24
	v_add_u32_e32 v76, v24, v62
	v_mov_b32_e32 v29, v81
	v_lshlrev_b32_e32 v64, 7, v76
	v_lshl_add_u64 v[28:29], v[28:29], 1, s[0:1]
	v_or_b32_e32 v32, v25, v64
	global_load_ushort v88, v[28:29], off
	v_max_i32_e32 v24, 1, v32
	v_min_i32_e32 v28, 0x3ffb, v32
	v_add_u32_e32 v28, 4, v28
	v_lshlrev_b32_e32 v24, 1, v24
	v_mov_b32_e32 v29, v81
	global_load_ushort v77, v24, s[0:1] offset:-2
	v_lshl_add_u64 v[28:29], v[28:29], 1, s[0:1]
	v_or_b32_e32 v24, 16, v32
	global_load_ushort v78, v[28:29], off
	v_max_i32_e32 v29, 1, v24
	v_min_i32_e32 v24, 0x3ffb, v24
	v_add_u32_e32 v28, 4, v24
	v_lshlrev_b32_e32 v24, 1, v29
	global_load_ushort v74, v24, s[0:1] offset:-2
	v_or_b32_e32 v24, 32, v32
	v_max_i32_e32 v59, 1, v24
	v_min_i32_e32 v24, 0x3ffb, v24
	v_add_u32_e32 v58, 4, v24
	v_lshlrev_b32_e32 v24, 1, v59
	v_mov_b32_e32 v59, v81
	global_load_ushort v67, v24, s[0:1] offset:-2
	v_lshl_add_u64 v[58:59], v[58:59], 1, s[0:1]
	v_or_b32_e32 v24, 48, v32
	v_mov_b32_e32 v27, v81
	global_load_ushort v73, v[58:59], off
	v_max_i32_e32 v59, 1, v24
	v_min_i32_e32 v24, 0x3ffb, v24
	v_lshl_add_u64 v[26:27], v[26:27], 1, s[0:1]
	v_mov_b32_e32 v33, v81
	v_mov_b32_e32 v29, v81
	v_add_u32_e32 v58, 4, v24
	v_lshlrev_b32_e32 v24, 1, v59
	v_mov_b32_e32 v59, v81
	v_max_i32_e32 v5, 1, v80
	global_load_ushort v82, v[26:27], off
	v_lshl_add_u64 v[26:27], v[32:33], 1, s[0:1]
	v_lshl_add_u64 v[28:29], v[28:29], 1, s[0:1]
	v_lshl_add_u64 v[58:59], v[58:59], 1, s[0:1]
	v_lshlrev_b32_e32 v5, 1, v5
	global_load_dwordx2 v[34:35], v[26:27], off
	global_load_dwordx2 v[30:31], v[26:27], off offset:32
	global_load_ushort v75, v[28:29], off
	global_load_ushort v65, v24, s[0:1] offset:-2
	global_load_ushort v66, v[58:59], off
	v_lshl_add_u32 v24, v3, 6, s21
	global_load_dwordx2 v[28:29], v[26:27], off offset:64
	v_readlane_b32 s69, v253, 57
	global_load_dwordx2 v[26:27], v[26:27], off offset:96
	v_readlane_b32 s70, v253, 58
	global_load_ushort v5, v5, s[0:1] offset:-2
	v_readlane_b32 s71, v253, 59
	v_readlane_b32 s74, v253, 62
	v_readlane_b32 s75, v253, 63
	v_readlane_b32 s76, v254, 0
	v_readlane_b32 s77, v254, 1
	v_readlane_b32 s78, v254, 2
	v_readlane_b32 s79, v254, 3
	v_readlane_b32 s80, v254, 4
	v_readlane_b32 s81, v254, 5
	v_readlane_b32 s82, v254, 6
	v_readlane_b32 s83, v254, 7
	v_mad_u64_u32 v[58:59], s[6:7], v1, s85, v[24:25]
	v_lshlrev_b32_e32 v59, 1, v25
	v_add_u32_e32 v1, v58, v59
	s_waitcnt vmcnt(19)
	v_and_b32_e32 v121, 0xffff0000, v61
	v_bitop3_b32 v3, v25, s33, v72 bitop3:0xc8
	v_lshlrev_b32_e32 v61, 16, v61
	ds_read_b64 v[116:117], v1
	s_waitcnt vmcnt(0)
	v_lshlrev_b32_e32 v5, 16, v5
	v_cmp_ne_u32_e32 vcc, 0, v3
	v_mov_b32_e32 v120, v61
	v_lshlrev_b32_e32 v118, 16, v60
	v_cndmask_b32_e32 v123, 0, v5, vcc
	v_add_u32_e32 v3, 4, v80
	v_and_b32_e32 v60, 0xffff0000, v60
	v_mov_b32_e32 v122, v7
	v_pk_mul_f32 v[126:127], v[6:7], v[120:121] op_sel_hi:[0,1]
	v_and_b32_e32 v3, s33, v3
	v_pk_fma_f32 v[126:127], v[122:123], v[60:61], v[126:127] op_sel_hi:[0,1,1]
	v_mov_b32_e32 v122, v60
	v_lshlrev_b32_e32 v5, 16, v91
	v_cmp_ne_u32_e32 vcc, 0, v3
	v_pk_mul_f32 v[122:123], v[6:7], v[122:123]
	v_mov_b32_e32 v124, v121
	v_cndmask_b32_e32 v125, 0, v5, vcc
	v_pk_fma_f32 v[118:119], v[6:7], v[118:119], v[122:123] op_sel:[0,0,1] op_sel_hi:[1,0,0]
	v_pk_fma_f32 v[120:121], v[0:1], v[124:125], v[126:127] op_sel_hi:[0,1,1]
	s_waitcnt lgkmcnt(0)
	v_lshlrev_b32_e32 v124, 16, v116
	v_and_b32_e32 v125, 0xffff0000, v116
	v_pk_fma_f32 v[60:61], v[0:1], v[60:61], v[118:119] op_sel_hi:[0,1,1]
	v_pk_fma_f32 v[16:17], v[4:5], v[124:125], v[16:17] op_sel_hi:[0,1,1]
	v_pk_add_f32 v[60:61], v[2:3], v[60:61] op_sel_hi:[0,1]
	v_pk_mul_f32 v[16:17], v[60:61], v[16:17]
	v_lshlrev_b32_e32 v60, 16, v117
	v_and_b32_e32 v61, 0xffff0000, v117
	v_pk_add_f32 v[120:121], v[2:3], v[120:121] op_sel_hi:[0,1]
	v_pk_fma_f32 v[18:19], v[4:5], v[60:61], v[18:19] op_sel_hi:[0,1,1]
	v_pk_mul_f32 v[18:19], v[120:121], v[18:19]
	v_cvt_pk_bf16_f32 v16, v16, v17
	v_cvt_pk_bf16_f32 v17, v18, v19
	s_mov_b64 s[6:7], -1
	s_and_b64 vcc, exec, s[10:11]
	s_cbranch_vccz .LBB0_461
	v_lshl_add_u64 v[18:19], v[80:81], 1, s[14:15]
	v_mov_b32_e32 v160, v16
	v_mov_b32_e32 v161, v17
	s_mov_b64 s[6:7], 0

; #define LAS __attribute__((address_space(3)))
; #define GAS __attribute__((address_space(1)))
; __device__ __forceinline__ unsigned pk2(float lo, float hi) { const f32x2_t f = {lo, hi}; const bf16x2_t b = __builtin_convertvector(f, bf16x2_t); return __builtin_bit_cast(unsigned, b); }
; __device__ __forceinline__ float lo16(unsigned v) { return __uint_as_float(v << 16); }
; __device__ __forceinline__ float hi16(unsigned v) { return __uint_as_float(v & 0xffff0000u); }
; __device__ __forceinline__ void conv_item(const Params& P, int slice, int item, LAS unsigned char* lds) {
;     ...
;         for (int hh = 0; hh < 2; ++hh) {
;           const int n = 32 * (2 * wn + nt) + 16 * hh + l16, bk = n >> nbsh, bs = n & (nb - 1), Bo = bs * nblk + bk;
; #pragma unroll
;           for (int mt = 0; mt < 4; ++mt) {
;             const int s0 = 64 * wm + 16 * mt + 4 * kc, tok = Bo * 128 + s0;
;             LAS u32x2* zp = (LAS u32x2*)(Zs + Bo * ZBLK + bs * 32 + 2 * s0);
;             const u32x2 zv = *zp; const f32x4 gt = sc4_apply(gr[hh][mt], tok, L, w0, w1, w2, bb);
;             const f32x4 av = acc[mt][2 * nt + hh];
;             const float y0 = gt[0] * (av[0] + skip * lo16(zv.x)), y1 = gt[1] * (av[1] + skip * hi16(zv.x));
;             const float y2 = gt[2] * (av[2] + skip * lo16(zv.y)), y3 = gt[3] * (av[3] + skip * hi16(zv.y));
;             u32x2 o; o.x = pk2(y0, y1); o.y = pk2(y2, y3);
;             if (order == 0) *zp = o; else *(GAS u32x2*)(zt + (unsigned)tok) = o;
.LBB0_463:
	v_or_b32_e32 v60, 16, v25
	v_lshlrev_b32_e32 v61, 1, v60
	v_add_u32_e32 v91, v58, v61
	v_or_b32_e32 v80, v72, v60
	ds_read_b64 v[116:117], v91
	v_add_u32_e32 v80, 4, v80
	v_lshlrev_b32_e32 v125, 16, v57
	v_mov_b32_e32 v18, v6
	v_mov_b32_e32 v19, v6
	v_and_b32_e32 v119, 0xffff0000, v57
	v_and_b32_e32 v80, s33, v80
	v_and_b32_e32 v122, 0xffff0000, v56
	v_mov_b32_e32 v118, v125
	v_mov_b32_e32 v16, v7
	v_mov_b32_e32 v17, v7
	v_lshlrev_b32_e32 v90, 16, v90
	v_cmp_ne_u32_e32 vcc, 0, v80
	v_mov_b32_e32 v124, v122
	v_pk_mul_f32 v[126:127], v[18:19], v[118:119]
	v_mov_b32_e32 v1, v0
	v_cndmask_b32_e32 v121, 0, v90, vcc
	v_pk_fma_f32 v[126:127], v[16:17], v[124:125], v[126:127]
	v_mov_b32_e32 v120, v119
	v_mov_b32_e32 v5, v4
	v_and_b32_e32 v123, 16, v57
	v_pk_fma_f32 v[118:119], v[0:1], v[120:121], v[126:127]
	v_lshlrev_b32_e32 v57, 16, v56
	v_lshlrev_b32_e32 v56, 16, v89
	s_waitcnt lgkmcnt(0)
	v_lshlrev_b32_e32 v120, 16, v116
	v_and_b32_e32 v121, 0xffff0000, v116
	v_pk_fma_f32 v[20:21], v[4:5], v[120:121], v[20:21]
	v_pk_mov_b32 v[120:121], v[56:57], v[122:123] op_sel:[1,0]
	v_mov_b32_e32 v3, v2
	v_pk_mul_f32 v[120:121], v[18:19], v[120:121]
	v_pk_add_f32 v[118:119], v[2:3], v[118:119]
	v_pk_fma_f32 v[56:57], v[16:17], v[56:57], v[120:121]
	s_andn2_b64 vcc, exec, s[10:11]
	v_pk_fma_f32 v[56:57], v[0:1], v[124:125], v[56:57]
	s_mov_b64 s[8:9], -1
	v_pk_add_f32 v[56:57], v[2:3], v[56:57]
	s_nop 0
	v_pk_mul_f32 v[20:21], v[56:57], v[20:21]
	v_lshlrev_b32_e32 v56, 16, v117
	v_and_b32_e32 v57, 0xffff0000, v117
	v_pk_fma_f32 v[22:23], v[4:5], v[56:57], v[22:23]
	v_cvt_pk_bf16_f32 v20, v20, v21
	v_pk_mul_f32 v[22:23], v[118:119], v[22:23]
	s_nop 0
	v_cvt_pk_bf16_f32 v21, v22, v23
	v_cndmask_b32_e64 v22, 0, 1, s[10:11]
	v_cmp_ne_u32_e64 s[6:7], 1, v22
	s_cbranch_vccnz .LBB0_465
	v_add_u32_e32 v80, v72, v25
	v_lshl_add_u64 v[22:23], v[80:81], 1, s[14:15]
	s_mov_b64 s[8:9], 0
	v_mov_b32_e32 v162, v20
	v_mov_b32_e32 v163, v21
	v_bfe_u32 v166, v225, 4, 1
	v_mul_u32_u24_e32 v166, 24, v166
	v_mov_b32_e32 v167, 0
	v_lshl_add_u64 v[164:165], v[166:167], 0, v[22:23]
	s_nop 1
	v_permlane16_swap_b32_e32 v160, v162
	v_permlane16_swap_b32_e32 v161, v163
	global_store_dwordx4 v[164:165], v[160:163], off

; #define LAS __attribute__((address_space(3)))
; #define GAS __attribute__((address_space(1)))
; __device__ __forceinline__ unsigned pk2(float lo, float hi) { const f32x2_t f = {lo, hi}; const bf16x2_t b = __builtin_convertvector(f, bf16x2_t); return __builtin_bit_cast(unsigned, b); }
; __device__ __forceinline__ float lo16(unsigned v) { return __uint_as_float(v << 16); }
; __device__ __forceinline__ float hi16(unsigned v) { return __uint_as_float(v & 0xffff0000u); }
; __device__ __forceinline__ void conv_item(const Params& P, int slice, int item, LAS unsigned char* lds) {
;     ...
;         for (int hh = 0; hh < 2; ++hh) {
;           const int n = 32 * (2 * wn + nt) + 16 * hh + l16, bk = n >> nbsh, bs = n & (nb - 1), Bo = bs * nblk + bk;
; #pragma unroll
;           for (int mt = 0; mt < 4; ++mt) {
;             const int s0 = 64 * wm + 16 * mt + 4 * kc, tok = Bo * 128 + s0;
;             LAS u32x2* zp = (LAS u32x2*)(Zs + Bo * ZBLK + bs * 32 + 2 * s0);
;             const u32x2 zv = *zp; const f32x4 gt = sc4_apply(gr[hh][mt], tok, L, w0, w1, w2, bb);
;             const f32x4 av = acc[mt][2 * nt + hh];
;             const float y0 = gt[0] * (av[0] + skip * lo16(zv.x)), y1 = gt[1] * (av[1] + skip * hi16(zv.x));
;             const float y2 = gt[2] * (av[2] + skip * lo16(zv.y)), y3 = gt[3] * (av[3] + skip * hi16(zv.y));
;             u32x2 o; o.x = pk2(y0, y1); o.y = pk2(y2, y3);
;             if (order == 0) *zp = o; else *(GAS u32x2*)(zt + (unsigned)tok) = o;
.LBB0_467:
	v_lshl_or_b32 v56, v25, 1, 64
	v_add_u32_e32 v20, v58, v56
	ds_read_b64 v[22:23], v20
	v_lshlrev_b32_e32 v119, 16, v39
	v_and_b32_e32 v89, 0xffff0000, v39
	v_lshlrev_b32_e32 v91, 16, v88
	v_and_b32_e32 v116, 0xffff0000, v38
	v_mov_b32_e32 v88, v119
	v_mov_b32_e32 v118, v116
	v_mov_b32_e32 v90, v89
	v_pk_mul_f32 v[88:89], v[18:19], v[88:89]
	v_and_b32_e32 v117, 16, v39
	v_pk_fma_f32 v[88:89], v[16:17], v[118:119], v[88:89]
	v_lshlrev_b32_e32 v39, 16, v38
	v_pk_fma_f32 v[88:89], v[0:1], v[90:91], v[88:89]
	v_lshlrev_b32_e32 v38, 16, v83
	s_waitcnt lgkmcnt(0)
	v_lshlrev_b32_e32 v90, 16, v22
	v_and_b32_e32 v91, 0xffff0000, v22
	v_pk_fma_f32 v[12:13], v[4:5], v[90:91], v[12:13]
	v_pk_mov_b32 v[90:91], v[38:39], v[116:117] op_sel:[1,0]
	v_lshlrev_b32_e32 v22, 16, v23
	v_pk_mul_f32 v[90:91], v[18:19], v[90:91]
	v_and_b32_e32 v23, 0xffff0000, v23
	v_pk_fma_f32 v[38:39], v[16:17], v[38:39], v[90:91]
	v_pk_add_f32 v[88:89], v[2:3], v[88:89]
	v_pk_fma_f32 v[38:39], v[0:1], v[118:119], v[38:39]
	v_pk_fma_f32 v[14:15], v[4:5], v[22:23], v[14:15]
	v_pk_add_f32 v[38:39], v[2:3], v[38:39]
	v_pk_mul_f32 v[14:15], v[88:89], v[14:15]
	v_pk_mul_f32 v[12:13], v[38:39], v[12:13]
	s_and_b64 vcc, exec, s[6:7]
	v_cvt_pk_bf16_f32 v12, v12, v13
	v_cvt_pk_bf16_f32 v13, v14, v15
	s_mov_b64 s[8:9], -1
	s_cbranch_vccnz .LBB0_469
	v_add_u32_e32 v80, v72, v25
	v_lshl_add_u64 v[14:15], v[80:81], 1, s[14:15]
	s_mov_b64 s[8:9], 0
	v_mov_b32_e32 v160, v12
	v_mov_b32_e32 v161, v13

; #define LAS __attribute__((address_space(3)))
; #define GAS __attribute__((address_space(1)))
; __device__ __forceinline__ unsigned pk2(float lo, float hi) { const f32x2_t f = {lo, hi}; const bf16x2_t b = __builtin_convertvector(f, bf16x2_t); return __builtin_bit_cast(unsigned, b); }
; __device__ __forceinline__ float lo16(unsigned v) { return __uint_as_float(v << 16); }
; __device__ __forceinline__ float hi16(unsigned v) { return __uint_as_float(v & 0xffff0000u); }
; __device__ __forceinline__ void conv_item(const Params& P, int slice, int item, LAS unsigned char* lds) {
;     ...
;         for (int hh = 0; hh < 2; ++hh) {
;           const int n = 32 * (2 * wn + nt) + 16 * hh + l16, bk = n >> nbsh, bs = n & (nb - 1), Bo = bs * nblk + bk;
; #pragma unroll
;           for (int mt = 0; mt < 4; ++mt) {
;             const int s0 = 64 * wm + 16 * mt + 4 * kc, tok = Bo * 128 + s0;
;             LAS u32x2* zp = (LAS u32x2*)(Zs + Bo * ZBLK + bs * 32 + 2 * s0);
;             const u32x2 zv = *zp; const f32x4 gt = sc4_apply(gr[hh][mt], tok, L, w0, w1, w2, bb);
;             const f32x4 av = acc[mt][2 * nt + hh];
;             const float y0 = gt[0] * (av[0] + skip * lo16(zv.x)), y1 = gt[1] * (av[1] + skip * hi16(zv.x));
;             const float y2 = gt[2] * (av[2] + skip * lo16(zv.y)), y3 = gt[3] * (av[3] + skip * hi16(zv.y));
;             u32x2 o; o.x = pk2(y0, y1); o.y = pk2(y2, y3);
;             if (order == 0) *zp = o; else *(GAS u32x2*)(zt + (unsigned)tok) = o;
.LBB0_471:
	v_or_b32_e32 v38, 48, v25
	v_or_b32_e32 v13, v72, v38
	v_lshlrev_b32_e32 v39, 1, v38
	v_add_u32_e32 v12, v58, v39
	v_add_u32_e32 v13, 4, v13
	ds_read_b64 v[14:15], v12
	v_and_b32_e32 v13, s33, v13
	v_lshlrev_b32_e32 v20, 16, v82
	v_cmp_ne_u32_e32 vcc, 0, v13
	v_lshlrev_b32_e32 v89, 16, v37
	v_and_b32_e32 v21, 0xffff0000, v37
	v_cndmask_b32_e32 v23, 0, v20, vcc
	v_and_b32_e32 v82, 0xffff0000, v36
	v_mov_b32_e32 v20, v89
	v_mov_b32_e32 v88, v82
	v_pk_mul_f32 v[90:91], v[18:19], v[20:21]
	v_mov_b32_e32 v22, v21
	v_pk_fma_f32 v[90:91], v[16:17], v[88:89], v[90:91]
	v_and_b32_e32 v83, 16, v37
	v_pk_fma_f32 v[20:21], v[0:1], v[22:23], v[90:91]
	v_lshlrev_b32_e32 v23, 16, v36
	v_lshlrev_b32_e32 v22, 16, v79
	s_waitcnt lgkmcnt(0)
	v_lshlrev_b32_e32 v36, 16, v14
	v_and_b32_e32 v37, 0xffff0000, v14
	v_pk_fma_f32 v[8:9], v[4:5], v[36:37], v[8:9]
	v_pk_mov_b32 v[36:37], v[22:23], v[82:83] op_sel:[1,0]
	v_lshlrev_b32_e32 v14, 16, v15
	v_pk_mul_f32 v[36:37], v[18:19], v[36:37]
	v_and_b32_e32 v15, 0xffff0000, v15
	v_pk_fma_f32 v[22:23], v[16:17], v[22:23], v[36:37]
	v_pk_add_f32 v[20:21], v[2:3], v[20:21]
	v_pk_fma_f32 v[22:23], v[0:1], v[88:89], v[22:23]
	v_pk_fma_f32 v[10:11], v[4:5], v[14:15], v[10:11]
	v_pk_add_f32 v[22:23], v[2:3], v[22:23]
	v_pk_mul_f32 v[10:11], v[20:21], v[10:11]
	v_pk_mul_f32 v[8:9], v[22:23], v[8:9]
	s_and_b64 vcc, exec, s[6:7]
	v_cvt_pk_bf16_f32 v8, v8, v9
	v_cvt_pk_bf16_f32 v9, v10, v11
	s_mov_b64 s[8:9], -1
	s_cbranch_vccnz .LBB0_473
	v_add_u32_e32 v80, v72, v25
	v_lshl_add_u64 v[10:11], v[80:81], 1, s[14:15]
	s_mov_b64 s[8:9], 0
	v_mov_b32_e32 v162, v8
	v_mov_b32_e32 v163, v9
	v_bfe_u32 v166, v225, 4, 1
	v_mul_u32_u24_e32 v166, 24, v166
	v_mov_b32_e32 v167, 0
	v_lshl_add_u64 v[164:165], v[166:167], 0, v[10:11]
	s_nop 1
	v_permlane16_swap_b32_e32 v160, v162
	v_permlane16_swap_b32_e32 v161, v163
	global_store_dwordx4 v[164:165], v[160:163], off offset:64

; #define LAS __attribute__((address_space(3)))
; #define GAS __attribute__((address_space(1)))
; __device__ __forceinline__ unsigned pk2(float lo, float hi) { const f32x2_t f = {lo, hi}; const bf16x2_t b = __builtin_convertvector(f, bf16x2_t); return __builtin_bit_cast(unsigned, b); }
; __device__ __forceinline__ float lo16(unsigned v) { return __uint_as_float(v << 16); }
; __device__ __forceinline__ float hi16(unsigned v) { return __uint_as_float(v & 0xffff0000u); }
; __device__ __forceinline__ void conv_item(const Params& P, int slice, int item, LAS unsigned char* lds) {
;     ...
;         for (int hh = 0; hh < 2; ++hh) {
;           const int n = 32 * (2 * wn + nt) + 16 * hh + l16, bk = n >> nbsh, bs = n & (nb - 1), Bo = bs * nblk + bk;
; #pragma unroll
;           for (int mt = 0; mt < 4; ++mt) {
;             const int s0 = 64 * wm + 16 * mt + 4 * kc, tok = Bo * 128 + s0;
;             LAS u32x2* zp = (LAS u32x2*)(Zs + Bo * ZBLK + bs * 32 + 2 * s0);
;             const u32x2 zv = *zp; const f32x4 gt = sc4_apply(gr[hh][mt], tok, L, w0, w1, w2, bb);
;             const f32x4 av = acc[mt][2 * nt + hh];
;             const float y0 = gt[0] * (av[0] + skip * lo16(zv.x)), y1 = gt[1] * (av[1] + skip * hi16(zv.x));
;             const float y2 = gt[2] * (av[2] + skip * lo16(zv.y)), y3 = gt[3] * (av[3] + skip * hi16(zv.y));
;             u32x2 o; o.x = pk2(y0, y1); o.y = pk2(y2, y3);
;             if (order == 0) *zp = o; else *(GAS u32x2*)(zt + (unsigned)tok) = o;
.LBB0_475:
	v_mad_u64_u32 v[8:9], s[8:9], v76, s85, v[24:25]
	v_and_b32_e32 v13, s33, v32
	v_add_u32_e32 v9, v8, v59
	v_cmp_ne_u32_e32 vcc, 0, v13
	v_add_u32_e32 v13, 4, v32
	ds_read_b64 v[10:11], v9
	v_lshlrev_b32_e32 v14, 16, v77
	v_and_b32_e32 v13, s33, v13
	v_lshlrev_b32_e32 v12, 16, v34
	v_and_b32_e32 v15, 0xffff0000, v35
	v_cndmask_b32_e32 v21, 0, v14, vcc
	v_lshlrev_b32_e32 v14, 16, v78
	v_cmp_ne_u32_e32 vcc, 0, v13
	v_and_b32_e32 v34, 0xffff0000, v34
	v_lshlrev_b32_e32 v35, 16, v35
	v_cndmask_b32_e32 v23, 0, v14, vcc
	v_mov_b32_e32 v14, v35
	v_mov_b32_e32 v20, v34
	v_pk_mul_f32 v[36:37], v[18:19], v[14:15]
	v_pk_mul_f32 v[20:21], v[6:7], v[20:21]
	v_pk_fma_f32 v[36:37], v[16:17], v[34:35], v[36:37]
	v_mov_b32_e32 v22, v15
	v_pk_fma_f32 v[12:13], v[6:7], v[12:13], v[20:21] op_sel:[0,0,1] op_sel_hi:[1,0,0]
	v_pk_fma_f32 v[14:15], v[0:1], v[22:23], v[36:37]
	s_waitcnt lgkmcnt(0)
	v_lshlrev_b32_e32 v22, 16, v10
	v_and_b32_e32 v23, 0xffff0000, v10
	v_pk_fma_f32 v[12:13], v[0:1], v[34:35], v[12:13]
	v_lshlrev_b32_e32 v10, 16, v11
	v_and_b32_e32 v11, 0xffff0000, v11
	v_pk_add_f32 v[14:15], v[2:3], v[14:15]
	v_pk_fma_f32 v[22:23], v[4:5], v[22:23], v[52:53]
	v_pk_add_f32 v[12:13], v[2:3], v[12:13]
	v_pk_fma_f32 v[10:11], v[4:5], v[10:11], v[54:55]
	v_pk_mul_f32 v[12:13], v[12:13], v[22:23]
	v_pk_mul_f32 v[14:15], v[14:15], v[10:11]
	v_cvt_pk_bf16_f32 v10, v12, v13
	v_cvt_pk_bf16_f32 v11, v14, v15
	s_and_b64 vcc, exec, s[6:7]
	s_mov_b64 s[8:9], -1
	s_cbranch_vccnz .LBB0_477
	v_lshl_add_u64 v[12:13], v[32:33], 1, s[14:15]
	s_mov_b64 s[8:9], 0
	v_mov_b32_e32 v160, v10
	v_mov_b32_e32 v161, v11

; #define LAS __attribute__((address_space(3)))
; #define GAS __attribute__((address_space(1)))
; __device__ __forceinline__ unsigned pk2(float lo, float hi) { const f32x2_t f = {lo, hi}; const bf16x2_t b = __builtin_convertvector(f, bf16x2_t); return __builtin_bit_cast(unsigned, b); }
; __device__ __forceinline__ float lo16(unsigned v) { return __uint_as_float(v << 16); }
; __device__ __forceinline__ float hi16(unsigned v) { return __uint_as_float(v & 0xffff0000u); }
; __device__ __forceinline__ void conv_item(const Params& P, int slice, int item, LAS unsigned char* lds) {
;     ...
;         for (int hh = 0; hh < 2; ++hh) {
;           const int n = 32 * (2 * wn + nt) + 16 * hh + l16, bk = n >> nbsh, bs = n & (nb - 1), Bo = bs * nblk + bk;
; #pragma unroll
;           for (int mt = 0; mt < 4; ++mt) {
;             const int s0 = 64 * wm + 16 * mt + 4 * kc, tok = Bo * 128 + s0;
;             LAS u32x2* zp = (LAS u32x2*)(Zs + Bo * ZBLK + bs * 32 + 2 * s0);
;             const u32x2 zv = *zp; const f32x4 gt = sc4_apply(gr[hh][mt], tok, L, w0, w1, w2, bb);
;             const f32x4 av = acc[mt][2 * nt + hh];
;             const float y0 = gt[0] * (av[0] + skip * lo16(zv.x)), y1 = gt[1] * (av[1] + skip * hi16(zv.x));
;             const float y2 = gt[2] * (av[2] + skip * lo16(zv.y)), y3 = gt[3] * (av[3] + skip * hi16(zv.y));
;             u32x2 o; o.x = pk2(y0, y1); o.y = pk2(y2, y3);
;             if (order == 0) *zp = o; else *(GAS u32x2*)(zt + (unsigned)tok) = o;
.LBB0_479:
	v_or_b32_e32 v12, v64, v60
	v_add_u32_e32 v12, 4, v12
	v_and_b32_e32 v12, s33, v12
	v_lshlrev_b32_e32 v23, 16, v31
	v_and_b32_e32 v13, 0xffff0000, v31
	v_cmp_ne_u32_e32 vcc, 0, v12
	v_and_b32_e32 v20, 0xffff0000, v30
	v_mov_b32_e32 v12, v23
	v_add_u32_e32 v9, v8, v61
	v_lshlrev_b32_e32 v14, 16, v75
	v_mov_b32_e32 v22, v20
	v_pk_mul_f32 v[32:33], v[18:19], v[12:13]
	ds_read_b64 v[10:11], v9
	v_cndmask_b32_e32 v15, 0, v14, vcc
	v_pk_fma_f32 v[32:33], v[16:17], v[22:23], v[32:33]
	v_mov_b32_e32 v14, v13
	v_and_b32_e32 v21, 16, v31
	v_pk_fma_f32 v[12:13], v[0:1], v[14:15], v[32:33]
	v_lshlrev_b32_e32 v15, 16, v30
	v_lshlrev_b32_e32 v14, 16, v74
	v_pk_mov_b32 v[20:21], v[14:15], v[20:21] op_sel:[1,0]
	s_waitcnt lgkmcnt(0)
	v_lshlrev_b32_e32 v30, 16, v10
	v_pk_mul_f32 v[20:21], v[18:19], v[20:21]
	v_and_b32_e32 v31, 0xffff0000, v10
	v_pk_fma_f32 v[14:15], v[16:17], v[14:15], v[20:21]
	v_lshlrev_b32_e32 v10, 16, v11
	v_pk_fma_f32 v[14:15], v[0:1], v[22:23], v[14:15]
	v_and_b32_e32 v11, 0xffff0000, v11
	v_pk_add_f32 v[12:13], v[2:3], v[12:13]
	v_pk_fma_f32 v[30:31], v[4:5], v[30:31], v[48:49]
	v_pk_add_f32 v[14:15], v[2:3], v[14:15]
	v_pk_fma_f32 v[10:11], v[4:5], v[10:11], v[50:51]
	v_pk_mul_f32 v[14:15], v[14:15], v[30:31]
	v_pk_mul_f32 v[12:13], v[12:13], v[10:11]
	v_cvt_pk_bf16_f32 v10, v14, v15
	v_cvt_pk_bf16_f32 v11, v12, v13
	s_and_b64 vcc, exec, s[6:7]
	s_mov_b64 s[8:9], -1
	s_cbranch_vccnz .LBB0_481
	v_add_u32_e32 v80, v64, v25
	v_lshl_add_u64 v[12:13], v[80:81], 1, s[14:15]
	s_mov_b64 s[8:9], 0
	v_mov_b32_e32 v162, v10
	v_mov_b32_e32 v163, v11
	v_bfe_u32 v166, v225, 4, 1
	v_mul_u32_u24_e32 v166, 24, v166
	v_mov_b32_e32 v167, 0
	v_lshl_add_u64 v[164:165], v[166:167], 0, v[12:13]
	s_nop 1
	v_permlane16_swap_b32_e32 v160, v162
	v_permlane16_swap_b32_e32 v161, v163
	global_store_dwordx4 v[164:165], v[160:163], off

; #define LAS __attribute__((address_space(3)))
; #define GAS __attribute__((address_space(1)))
; __device__ __forceinline__ unsigned pk2(float lo, float hi) { const f32x2_t f = {lo, hi}; const bf16x2_t b = __builtin_convertvector(f, bf16x2_t); return __builtin_bit_cast(unsigned, b); }
; __device__ __forceinline__ float lo16(unsigned v) { return __uint_as_float(v << 16); }
; __device__ __forceinline__ float hi16(unsigned v) { return __uint_as_float(v & 0xffff0000u); }
; __device__ __forceinline__ void conv_item(const Params& P, int slice, int item, LAS unsigned char* lds) {
;     ...
;         for (int hh = 0; hh < 2; ++hh) {
;           const int n = 32 * (2 * wn + nt) + 16 * hh + l16, bk = n >> nbsh, bs = n & (nb - 1), Bo = bs * nblk + bk;
; #pragma unroll
;           for (int mt = 0; mt < 4; ++mt) {
;             const int s0 = 64 * wm + 16 * mt + 4 * kc, tok = Bo * 128 + s0;
;             LAS u32x2* zp = (LAS u32x2*)(Zs + Bo * ZBLK + bs * 32 + 2 * s0);
;             const u32x2 zv = *zp; const f32x4 gt = sc4_apply(gr[hh][mt], tok, L, w0, w1, w2, bb);
;             const f32x4 av = acc[mt][2 * nt + hh];
;             const float y0 = gt[0] * (av[0] + skip * lo16(zv.x)), y1 = gt[1] * (av[1] + skip * hi16(zv.x));
;             const float y2 = gt[2] * (av[2] + skip * lo16(zv.y)), y3 = gt[3] * (av[3] + skip * hi16(zv.y));
;             u32x2 o; o.x = pk2(y0, y1); o.y = pk2(y2, y3);
;             if (order == 0) *zp = o; else *(GAS u32x2*)(zt + (unsigned)tok) = o;
.LBB0_483:
	v_lshlrev_b32_e32 v23, 16, v29
	v_and_b32_e32 v13, 0xffff0000, v29
	v_and_b32_e32 v20, 0xffff0000, v28
	v_mov_b32_e32 v12, v23
	v_add_u32_e32 v9, v8, v56
	v_mov_b32_e32 v22, v20
	v_mov_b32_e32 v14, v13
	v_pk_mul_f32 v[12:13], v[18:19], v[12:13]
	ds_read_b64 v[10:11], v9
	v_lshlrev_b32_e32 v15, 16, v73
	v_pk_fma_f32 v[12:13], v[16:17], v[22:23], v[12:13]
	v_and_b32_e32 v21, 16, v29
	v_pk_fma_f32 v[12:13], v[0:1], v[14:15], v[12:13]
	v_lshlrev_b32_e32 v15, 16, v28
	v_lshlrev_b32_e32 v14, 16, v67
	v_pk_mov_b32 v[20:21], v[14:15], v[20:21] op_sel:[1,0]
	s_waitcnt lgkmcnt(0)
	v_lshlrev_b32_e32 v28, 16, v10
	v_pk_mul_f32 v[20:21], v[18:19], v[20:21]
	v_and_b32_e32 v29, 0xffff0000, v10
	v_pk_fma_f32 v[14:15], v[16:17], v[14:15], v[20:21]
	v_lshlrev_b32_e32 v10, 16, v11
	v_pk_fma_f32 v[14:15], v[0:1], v[22:23], v[14:15]
	v_and_b32_e32 v11, 0xffff0000, v11
	v_pk_add_f32 v[12:13], v[2:3], v[12:13]
	v_pk_fma_f32 v[28:29], v[4:5], v[28:29], v[44:45]
	v_pk_add_f32 v[14:15], v[2:3], v[14:15]
	v_pk_fma_f32 v[10:11], v[4:5], v[10:11], v[46:47]
	v_pk_mul_f32 v[14:15], v[14:15], v[28:29]
	v_pk_mul_f32 v[12:13], v[12:13], v[10:11]
	v_cvt_pk_bf16_f32 v10, v14, v15
	v_cvt_pk_bf16_f32 v11, v12, v13
	s_and_b64 vcc, exec, s[6:7]
	s_mov_b64 s[8:9], -1
	s_cbranch_vccnz .LBB0_485
	v_add_u32_e32 v80, v64, v25
	v_lshl_add_u64 v[12:13], v[80:81], 1, s[14:15]
	s_mov_b64 s[8:9], 0
	v_mov_b32_e32 v160, v10
	v_mov_b32_e32 v161, v11

; #define LAS __attribute__((address_space(3)))
; #define GAS __attribute__((address_space(1)))
; __device__ __forceinline__ unsigned pk2(float lo, float hi) { const f32x2_t f = {lo, hi}; const bf16x2_t b = __builtin_convertvector(f, bf16x2_t); return __builtin_bit_cast(unsigned, b); }
; __device__ __forceinline__ float lo16(unsigned v) { return __uint_as_float(v << 16); }
; __device__ __forceinline__ float hi16(unsigned v) { return __uint_as_float(v & 0xffff0000u); }
; __device__ __forceinline__ void conv_item(const Params& P, int slice, int item, LAS unsigned char* lds) {
;     ...
;         for (int hh = 0; hh < 2; ++hh) {
;           const int n = 32 * (2 * wn + nt) + 16 * hh + l16, bk = n >> nbsh, bs = n & (nb - 1), Bo = bs * nblk + bk;
; #pragma unroll
;           for (int mt = 0; mt < 4; ++mt) {
;             const int s0 = 64 * wm + 16 * mt + 4 * kc, tok = Bo * 128 + s0;
;             LAS u32x2* zp = (LAS u32x2*)(Zs + Bo * ZBLK + bs * 32 + 2 * s0);
;             const u32x2 zv = *zp; const f32x4 gt = sc4_apply(gr[hh][mt], tok, L, w0, w1, w2, bb);
;             const f32x4 av = acc[mt][2 * nt + hh];
;             const float y0 = gt[0] * (av[0] + skip * lo16(zv.x)), y1 = gt[1] * (av[1] + skip * hi16(zv.x));
;             const float y2 = gt[2] * (av[2] + skip * lo16(zv.y)), y3 = gt[3] * (av[3] + skip * hi16(zv.y));
;             u32x2 o; o.x = pk2(y0, y1); o.y = pk2(y2, y3);
;             if (order == 0) *zp = o; else *(GAS u32x2*)(zt + (unsigned)tok) = o;
.LBB0_487:
	v_or_b32_e32 v11, v64, v38
	v_add_u32_e32 v11, 4, v11
	v_and_b32_e32 v11, s33, v11
	v_lshlrev_b32_e32 v12, 16, v66
	v_cmp_ne_u32_e32 vcc, 0, v11
	v_lshlrev_b32_e32 v23, 16, v27
	v_and_b32_e32 v13, 0xffff0000, v27
	v_cndmask_b32_e32 v15, 0, v12, vcc
	v_and_b32_e32 v20, 0xffff0000, v26
	v_mov_b32_e32 v12, v23
	v_add_u32_e32 v10, v8, v39
	v_mov_b32_e32 v22, v20
	v_pk_mul_f32 v[28:29], v[18:19], v[12:13]
	ds_read_b64 v[8:9], v10
	v_pk_fma_f32 v[28:29], v[16:17], v[22:23], v[28:29]
	v_mov_b32_e32 v14, v13
	v_and_b32_e32 v21, 16, v27
	v_pk_fma_f32 v[12:13], v[0:1], v[14:15], v[28:29]
	v_lshlrev_b32_e32 v15, 16, v26
	v_lshlrev_b32_e32 v14, 16, v65
	v_pk_mov_b32 v[20:21], v[14:15], v[20:21] op_sel:[1,0]
	s_waitcnt lgkmcnt(0)
	v_lshlrev_b32_e32 v26, 16, v8
	v_pk_mul_f32 v[20:21], v[18:19], v[20:21]
	v_and_b32_e32 v27, 0xffff0000, v8
	v_pk_fma_f32 v[14:15], v[16:17], v[14:15], v[20:21]
	v_lshlrev_b32_e32 v8, 16, v9
	v_pk_fma_f32 v[14:15], v[0:1], v[22:23], v[14:15]
	v_and_b32_e32 v9, 0xffff0000, v9
	v_pk_add_f32 v[12:13], v[2:3], v[12:13]
	v_pk_fma_f32 v[26:27], v[4:5], v[26:27], v[40:41]
	v_pk_add_f32 v[14:15], v[2:3], v[14:15]
	v_pk_fma_f32 v[8:9], v[4:5], v[8:9], v[42:43]
	v_pk_mul_f32 v[14:15], v[14:15], v[26:27]
	v_pk_mul_f32 v[12:13], v[12:13], v[8:9]
	v_cvt_pk_bf16_f32 v8, v14, v15
	v_cvt_pk_bf16_f32 v9, v12, v13
	s_and_b64 vcc, exec, s[6:7]
	s_mov_b64 s[8:9], -1
	s_cbranch_vccnz .LBB0_489
	v_add_u32_e32 v80, v64, v25
	v_lshl_add_u64 v[12:13], v[80:81], 1, s[14:15]
	s_mov_b64 s[8:9], 0
	v_mov_b32_e32 v162, v8
	v_mov_b32_e32 v163, v9
	v_bfe_u32 v166, v225, 4, 1
	v_mul_u32_u24_e32 v166, 24, v166
	v_mov_b32_e32 v167, 0
	v_lshl_add_u64 v[164:165], v[166:167], 0, v[12:13]
	s_nop 1
	v_permlane16_swap_b32_e32 v160, v162
	v_permlane16_swap_b32_e32 v161, v163
	global_store_dwordx4 v[164:165], v[160:163], off offset:64

; #define LAS __attribute__((address_space(3)))
; #define GAS __attribute__((address_space(1)))
; __device__ __forceinline__ unsigned pk2(float lo, float hi) { const f32x2_t f = {lo, hi}; const bf16x2_t b = __builtin_convertvector(f, bf16x2_t); return __builtin_bit_cast(unsigned, b); }
; __device__ __forceinline__ float lo16(unsigned v) { return __uint_as_float(v << 16); }
; __device__ __forceinline__ float hi16(unsigned v) { return __uint_as_float(v & 0xffff0000u); }
; __device__ __forceinline__ void conv_item(const Params& P, int slice, int item, LAS unsigned char* lds) {
;     ...
;       for (int nt = 0; nt < 2; ++nt) {
;         Sc4Raw gr[2][4];
; #pragma unroll
;         for (int hh = 0; hh < 2; ++hh) {
;           const int n = 32 * (2 * wn + nt) + 16 * hh + l16, bk = n >> nbsh, bs = n & (nb - 1), Bo = bs * nblk + bk;
; #pragma unroll
;           for (int mt = 0; mt < 4; ++mt) gr[hh][mt] = sc4_load(grow, Bo * 128 + 64 * wm + 16 * mt + 4 * kc);
;         }
;         __builtin_amdgcn_sched_barrier(0);
; #pragma unroll
;         for (int hh = 0; hh < 2; ++hh) {
;           const int n = 32 * (2 * wn + nt) + 16 * hh + l16, bk = n >> nbsh, bs = n & (nb - 1), Bo = bs * nblk + bk;
; #pragma unroll
;           for (int mt = 0; mt < 4; ++mt) {
;             const int s0 = 64 * wm + 16 * mt + 4 * kc, tok = Bo * 128 + s0;
;             LAS u32x2* zp = (LAS u32x2*)(Zs + Bo * ZBLK + bs * 32 + 2 * s0);
;             const u32x2 zv = *zp; const f32x4 gt = sc4_apply(gr[hh][mt], tok, L, w0, w1, w2, bb);
;             const f32x4 av = acc[mt][2 * nt + hh];
;             const float y0 = gt[0] * (av[0] + skip * lo16(zv.x)), y1 = gt[1] * (av[1] + skip * hi16(zv.x));
;             const float y2 = gt[2] * (av[2] + skip * lo16(zv.y)), y3 = gt[3] * (av[3] + skip * hi16(zv.y));
;             u32x2 o; o.x = pk2(y0, y1); o.y = pk2(y2, y3);
;             if (order == 0) *zp = o; else *(GAS u32x2*)(zt + (unsigned)tok) = o;
.LBB0_491:
	v_or_b32_e32 v8, 32, v63
	v_ashrrev_i32_e32 v8, s94, v8
	v_add_u32_e32 v53, v8, v62
	v_lshlrev_b32_e32 v40, 7, v53
	v_or_b32_e32 v80, v25, v40
	v_max_i32_e32 v11, 1, v80
	v_min_i32_e32 v10, 0x3ffb, v80
	v_lshlrev_b32_e32 v11, 1, v11
	v_add_u32_e32 v10, 4, v10
	global_load_ushort v57, v11, s[0:1] offset:-2
	v_mov_b32_e32 v11, v81
	v_lshl_add_u64 v[10:11], v[10:11], 1, s[0:1]
	global_load_ushort v64, v[10:11], off
	v_or_b32_e32 v10, 16, v80
	v_max_i32_e32 v11, 1, v10
	v_min_i32_e32 v10, 0x3ffb, v10
	v_lshlrev_b32_e32 v11, 1, v11
	v_add_u32_e32 v10, 4, v10
	global_load_ushort v51, v11, s[0:1] offset:-2
	v_mov_b32_e32 v11, v81
	v_lshl_add_u64 v[10:11], v[10:11], 1, s[0:1]
	global_load_ushort v52, v[10:11], off
	v_or_b32_e32 v10, 32, v80
	v_max_i32_e32 v11, 1, v10
	v_min_i32_e32 v10, 0x3ffb, v10
	v_lshlrev_b32_e32 v11, 1, v11
	v_add_u32_e32 v10, 4, v10
	global_load_ushort v49, v11, s[0:1] offset:-2
	v_mov_b32_e32 v11, v81
	v_lshl_add_u64 v[10:11], v[10:11], 1, s[0:1]
	v_lshl_add_u64 v[8:9], v[80:81], 1, s[0:1]
	global_load_ushort v50, v[10:11], off
	v_or_b32_e32 v10, 48, v80
	global_load_dwordx2 v[32:33], v[8:9], off
	global_load_dwordx2 v[28:29], v[8:9], off offset:32
	global_load_dwordx2 v[26:27], v[8:9], off offset:64
	global_load_dwordx2 v[22:23], v[8:9], off offset:96
	v_max_i32_e32 v9, 1, v10
	v_min_i32_e32 v8, 0x3ffb, v10
	v_lshlrev_b32_e32 v9, 1, v9
	v_add_u32_e32 v8, 4, v8
	global_load_ushort v47, v9, s[0:1] offset:-2
	v_mov_b32_e32 v9, v81
	v_lshl_add_u64 v[8:9], v[8:9], 1, s[0:1]
	global_load_ushort v48, v[8:9], off
	v_or_b32_e32 v8, 48, v63
	v_ashrrev_i32_e32 v8, s94, v8
	v_add_u32_e32 v44, v8, v62
	v_lshlrev_b32_e32 v34, 7, v44
	v_or_b32_e32 v14, v25, v34
	v_or_b32_e32 v30, 32, v14
	v_max_i32_e32 v11, 1, v14
	v_max_i32_e32 v31, 1, v30
	v_min_i32_e32 v10, 0x3ffb, v14
	v_lshlrev_b32_e32 v11, 1, v11
	v_min_i32_e32 v30, 0x3ffb, v30
	v_lshlrev_b32_e32 v31, 1, v31
	v_add_u32_e32 v10, 4, v10
	global_load_ushort v45, v11, s[0:1] offset:-2
	v_mov_b32_e32 v11, v81
	v_add_u32_e32 v30, 4, v30
	global_load_ushort v37, v31, s[0:1] offset:-2
	v_mov_b32_e32 v31, v81
	v_lshl_add_u64 v[10:11], v[10:11], 1, s[0:1]
	v_lshl_add_u64 v[30:31], v[30:31], 1, s[0:1]
	global_load_ushort v46, v[10:11], off
	v_or_b32_e32 v10, 16, v14
	global_load_ushort v41, v[30:31], off
	v_or_b32_e32 v30, 48, v14
	v_max_i32_e32 v11, 1, v10
	v_max_i32_e32 v31, 1, v30
	v_min_i32_e32 v10, 0x3ffb, v10
	v_lshlrev_b32_e32 v11, 1, v11
	v_min_i32_e32 v30, 0x3ffb, v30
	v_lshlrev_b32_e32 v31, 1, v31
	v_mov_b32_e32 v15, v81
	v_add_u32_e32 v10, 4, v10
	global_load_ushort v42, v11, s[0:1] offset:-2
	v_mov_b32_e32 v11, v81
	v_add_u32_e32 v30, 4, v30
	global_load_ushort v35, v31, s[0:1] offset:-2
	v_mov_b32_e32 v31, v81
	v_lshl_add_u64 v[8:9], v[14:15], 1, s[0:1]
	v_lshl_add_u64 v[10:11], v[10:11], 1, s[0:1]
	v_lshl_add_u64 v[30:31], v[30:31], 1, s[0:1]
	global_load_dwordx2 v[20:21], v[8:9], off
	global_load_dwordx2 v[12:13], v[8:9], off offset:32
	global_load_ushort v43, v[10:11], off
	global_load_ushort v36, v[30:31], off
	s_nop 0
	global_load_dwordx2 v[10:11], v[8:9], off offset:64
	s_nop 0
	global_load_dwordx2 v[8:9], v[8:9], off offset:96
	v_mad_u64_u32 v[30:31], s[0:1], v53, s85, v[24:25]
	v_add_u32_e32 v31, v30, v59
	ds_read_b64 v[54:55], v31
	v_bitop3_b32 v53, v25, s33, v40 bitop3:0xc8
	s_waitcnt vmcnt(17)
	v_lshlrev_b32_e32 v58, 16, v32
	v_and_b32_e32 v63, 0xffff0000, v33
	v_lshlrev_b32_e32 v57, 16, v57
	v_cmp_ne_u32_e32 vcc, 0, v53
	v_add_u32_e32 v53, 4, v80
	v_and_b32_e32 v32, 0xffff0000, v32
	v_lshlrev_b32_e32 v33, 16, v33
	v_cndmask_b32_e32 v65, 0, v57, vcc
	v_and_b32_e32 v53, s33, v53
	v_lshlrev_b32_e32 v57, 16, v64
	v_mov_b32_e32 v62, v33
	v_mov_b32_e32 v64, v32
	v_cmp_ne_u32_e32 vcc, 0, v53
	v_pk_mul_f32 v[72:73], v[18:19], v[62:63]
	v_pk_mul_f32 v[64:65], v[6:7], v[64:65]
	v_cndmask_b32_e32 v67, 0, v57, vcc
	v_pk_fma_f32 v[72:73], v[16:17], v[32:33], v[72:73]
	v_mov_b32_e32 v66, v63
	v_pk_fma_f32 v[64:65], v[6:7], v[58:59], v[64:65] op_sel:[0,0,1] op_sel_hi:[1,0,0]
	v_pk_fma_f32 v[62:63], v[0:1], v[66:67], v[72:73]
	s_waitcnt lgkmcnt(0)
	v_lshlrev_b32_e32 v66, 16, v54
	v_and_b32_e32 v67, 0xffff0000, v54
	v_pk_fma_f32 v[32:33], v[0:1], v[32:33], v[64:65]
	v_lshlrev_b32_e32 v54, 16, v55
	v_and_b32_e32 v55, 0xffff0000, v55
	v_pk_add_f32 v[62:63], v[2:3], v[62:63]
	v_pk_fma_f32 v[66:67], v[4:5], v[66:67], v[92:93]
	v_pk_add_f32 v[32:33], v[2:3], v[32:33]
	v_pk_fma_f32 v[54:55], v[4:5], v[54:55], v[94:95]
	v_pk_mul_f32 v[32:33], v[32:33], v[66:67]
	v_pk_mul_f32 v[54:55], v[62:63], v[54:55]
	v_cvt_pk_bf16_f32 v32, v32, v33
	v_cvt_pk_bf16_f32 v33, v54, v55
	s_and_b64 vcc, exec, s[6:7]
	s_mov_b64 s[0:1], -1
	s_cbranch_vccnz .LBB0_493
	v_lshl_add_u64 v[54:55], v[80:81], 1, s[14:15]
	s_mov_b64 s[0:1], 0
	v_mov_b32_e32 v160, v32
	v_mov_b32_e32 v161, v33

; #define LAS __attribute__((address_space(3)))
; #define GAS __attribute__((address_space(1)))
; __device__ __forceinline__ unsigned pk2(float lo, float hi) { const f32x2_t f = {lo, hi}; const bf16x2_t b = __builtin_convertvector(f, bf16x2_t); return __builtin_bit_cast(unsigned, b); }
; __device__ __forceinline__ float lo16(unsigned v) { return __uint_as_float(v << 16); }
; __device__ __forceinline__ float hi16(unsigned v) { return __uint_as_float(v & 0xffff0000u); }
; __device__ __forceinline__ void conv_item(const Params& P, int slice, int item, LAS unsigned char* lds) {
;     ...
;         for (int hh = 0; hh < 2; ++hh) {
;           const int n = 32 * (2 * wn + nt) + 16 * hh + l16, bk = n >> nbsh, bs = n & (nb - 1), Bo = bs * nblk + bk;
; #pragma unroll
;           for (int mt = 0; mt < 4; ++mt) {
;             const int s0 = 64 * wm + 16 * mt + 4 * kc, tok = Bo * 128 + s0;
;             LAS u32x2* zp = (LAS u32x2*)(Zs + Bo * ZBLK + bs * 32 + 2 * s0);
;             const u32x2 zv = *zp; const f32x4 gt = sc4_apply(gr[hh][mt], tok, L, w0, w1, w2, bb);
;             const f32x4 av = acc[mt][2 * nt + hh];
;             const float y0 = gt[0] * (av[0] + skip * lo16(zv.x)), y1 = gt[1] * (av[1] + skip * hi16(zv.x));
;             const float y2 = gt[2] * (av[2] + skip * lo16(zv.y)), y3 = gt[3] * (av[3] + skip * hi16(zv.y));
;             u32x2 o; o.x = pk2(y0, y1); o.y = pk2(y2, y3);
;             if (order == 0) *zp = o; else *(GAS u32x2*)(zt + (unsigned)tok) = o;
.LBB0_495:
	v_or_b32_e32 v54, v40, v60
	v_add_u32_e32 v31, v30, v61
	v_add_u32_e32 v54, 4, v54
	ds_read_b64 v[32:33], v31
	v_and_b32_e32 v54, s33, v54
	s_waitcnt vmcnt(16)
	v_and_b32_e32 v53, 0xffff0000, v29
	v_lshlrev_b32_e32 v52, 16, v52
	v_cmp_ne_u32_e32 vcc, 0, v54
	v_and_b32_e32 v63, 16, v29
	v_and_b32_e32 v62, 0xffff0000, v28
	v_lshlrev_b32_e32 v65, 16, v29
	v_lshlrev_b32_e32 v29, 16, v28
	v_lshlrev_b32_e32 v28, 16, v51
	v_cndmask_b32_e32 v55, 0, v52, vcc
	v_mov_b32_e32 v64, v62
	v_mov_b32_e32 v52, v65
	v_pk_mov_b32 v[62:63], v[28:29], v[62:63] op_sel:[1,0]
	v_pk_mul_f32 v[66:67], v[18:19], v[52:53]
	v_pk_mul_f32 v[62:63], v[18:19], v[62:63]
	v_pk_fma_f32 v[66:67], v[16:17], v[64:65], v[66:67]
	v_mov_b32_e32 v54, v53
	v_pk_fma_f32 v[28:29], v[16:17], v[28:29], v[62:63]
	v_pk_fma_f32 v[52:53], v[0:1], v[54:55], v[66:67]
	s_waitcnt lgkmcnt(0)
	v_lshlrev_b32_e32 v54, 16, v32
	v_and_b32_e32 v55, 0xffff0000, v32
	v_pk_fma_f32 v[28:29], v[0:1], v[64:65], v[28:29]
	v_lshlrev_b32_e32 v32, 16, v33
	v_and_b32_e32 v33, 0xffff0000, v33
	v_pk_add_f32 v[52:53], v[2:3], v[52:53]
	v_pk_fma_f32 v[54:55], v[4:5], v[54:55], v[96:97]
	v_pk_add_f32 v[28:29], v[2:3], v[28:29]
	v_pk_fma_f32 v[32:33], v[4:5], v[32:33], v[98:99]
	v_pk_mul_f32 v[28:29], v[28:29], v[54:55]
	v_pk_mul_f32 v[32:33], v[52:53], v[32:33]
	v_cvt_pk_bf16_f32 v28, v28, v29
	v_cvt_pk_bf16_f32 v29, v32, v33
	s_and_b64 vcc, exec, s[6:7]
	s_mov_b64 s[0:1], -1
	s_cbranch_vccnz .LBB0_497
	v_add_u32_e32 v80, v40, v25
	v_lshl_add_u64 v[32:33], v[80:81], 1, s[14:15]
	s_mov_b64 s[0:1], 0
	v_mov_b32_e32 v162, v28
	v_mov_b32_e32 v163, v29
	v_bfe_u32 v166, v225, 4, 1
	v_mul_u32_u24_e32 v166, 24, v166
	v_mov_b32_e32 v167, 0
	v_lshl_add_u64 v[164:165], v[166:167], 0, v[32:33]
	s_nop 1
	v_permlane16_swap_b32_e32 v160, v162
	v_permlane16_swap_b32_e32 v161, v163
	global_store_dwordx4 v[164:165], v[160:163], off

; #define LAS __attribute__((address_space(3)))
; #define GAS __attribute__((address_space(1)))
; __device__ __forceinline__ unsigned pk2(float lo, float hi) { const f32x2_t f = {lo, hi}; const bf16x2_t b = __builtin_convertvector(f, bf16x2_t); return __builtin_bit_cast(unsigned, b); }
; __device__ __forceinline__ float lo16(unsigned v) { return __uint_as_float(v << 16); }
; __device__ __forceinline__ float hi16(unsigned v) { return __uint_as_float(v & 0xffff0000u); }
; __device__ __forceinline__ void conv_item(const Params& P, int slice, int item, LAS unsigned char* lds) {
;     ...
;         for (int hh = 0; hh < 2; ++hh) {
;           const int n = 32 * (2 * wn + nt) + 16 * hh + l16, bk = n >> nbsh, bs = n & (nb - 1), Bo = bs * nblk + bk;
; #pragma unroll
;           for (int mt = 0; mt < 4; ++mt) {
;             const int s0 = 64 * wm + 16 * mt + 4 * kc, tok = Bo * 128 + s0;
;             LAS u32x2* zp = (LAS u32x2*)(Zs + Bo * ZBLK + bs * 32 + 2 * s0);
;             const u32x2 zv = *zp; const f32x4 gt = sc4_apply(gr[hh][mt], tok, L, w0, w1, w2, bb);
;             const f32x4 av = acc[mt][2 * nt + hh];
;             const float y0 = gt[0] * (av[0] + skip * lo16(zv.x)), y1 = gt[1] * (av[1] + skip * hi16(zv.x));
;             const float y2 = gt[2] * (av[2] + skip * lo16(zv.y)), y3 = gt[3] * (av[3] + skip * hi16(zv.y));
;             u32x2 o; o.x = pk2(y0, y1); o.y = pk2(y2, y3);
;             if (order == 0) *zp = o; else *(GAS u32x2*)(zt + (unsigned)tok) = o;
.LBB0_499:
	v_add_u32_e32 v28, v30, v56
	ds_read_b64 v[32:33], v28
	s_waitcnt vmcnt(15)
	v_and_b32_e32 v51, 0xffff0000, v27
	v_and_b32_e32 v55, 16, v27
	v_and_b32_e32 v54, 0xffff0000, v26
	v_lshlrev_b32_e32 v63, 16, v27
	v_lshlrev_b32_e32 v27, 16, v26
	v_lshlrev_b32_e32 v26, 16, v49
	v_lshlrev_b32_e32 v53, 16, v50
	v_mov_b32_e32 v62, v54
	v_mov_b32_e32 v50, v63
	v_pk_mov_b32 v[54:55], v[26:27], v[54:55] op_sel:[1,0]
	v_mov_b32_e32 v52, v51
	v_pk_mul_f32 v[50:51], v[18:19], v[50:51]
	v_pk_mul_f32 v[54:55], v[18:19], v[54:55]
	v_pk_fma_f32 v[50:51], v[16:17], v[62:63], v[50:51]
	v_pk_fma_f32 v[26:27], v[16:17], v[26:27], v[54:55]
	v_pk_fma_f32 v[50:51], v[0:1], v[52:53], v[50:51]
	s_waitcnt lgkmcnt(0)
	v_lshlrev_b32_e32 v52, 16, v32
	v_and_b32_e32 v53, 0xffff0000, v32
	v_pk_fma_f32 v[26:27], v[0:1], v[62:63], v[26:27]
	v_lshlrev_b32_e32 v32, 16, v33
	v_and_b32_e32 v33, 0xffff0000, v33
	v_pk_add_f32 v[50:51], v[2:3], v[50:51]
	v_pk_fma_f32 v[52:53], v[4:5], v[52:53], v[84:85]
	v_pk_add_f32 v[26:27], v[2:3], v[26:27]
	v_pk_fma_f32 v[32:33], v[4:5], v[32:33], v[86:87]
	v_pk_mul_f32 v[26:27], v[26:27], v[52:53]
	v_pk_mul_f32 v[32:33], v[50:51], v[32:33]
	v_cvt_pk_bf16_f32 v26, v26, v27
	v_cvt_pk_bf16_f32 v27, v32, v33
	s_and_b64 vcc, exec, s[6:7]
	s_mov_b64 s[0:1], -1
	s_cbranch_vccnz .LBB0_501
	v_add_u32_e32 v80, v40, v25
	v_lshl_add_u64 v[32:33], v[80:81], 1, s[14:15]
	s_mov_b64 s[0:1], 0
	v_mov_b32_e32 v160, v26
	v_mov_b32_e32 v161, v27

; #define LAS __attribute__((address_space(3)))
; #define GAS __attribute__((address_space(1)))
; __device__ __forceinline__ unsigned pk2(float lo, float hi) { const f32x2_t f = {lo, hi}; const bf16x2_t b = __builtin_convertvector(f, bf16x2_t); return __builtin_bit_cast(unsigned, b); }
; __device__ __forceinline__ float lo16(unsigned v) { return __uint_as_float(v << 16); }
; __device__ __forceinline__ float hi16(unsigned v) { return __uint_as_float(v & 0xffff0000u); }
; __device__ __forceinline__ void conv_item(const Params& P, int slice, int item, LAS unsigned char* lds) {
;     ...
;         for (int hh = 0; hh < 2; ++hh) {
;           const int n = 32 * (2 * wn + nt) + 16 * hh + l16, bk = n >> nbsh, bs = n & (nb - 1), Bo = bs * nblk + bk;
; #pragma unroll
;           for (int mt = 0; mt < 4; ++mt) {
;             const int s0 = 64 * wm + 16 * mt + 4 * kc, tok = Bo * 128 + s0;
;             LAS u32x2* zp = (LAS u32x2*)(Zs + Bo * ZBLK + bs * 32 + 2 * s0);
;             const u32x2 zv = *zp; const f32x4 gt = sc4_apply(gr[hh][mt], tok, L, w0, w1, w2, bb);
;             const f32x4 av = acc[mt][2 * nt + hh];
;             const float y0 = gt[0] * (av[0] + skip * lo16(zv.x)), y1 = gt[1] * (av[1] + skip * hi16(zv.x));
;             const float y2 = gt[2] * (av[2] + skip * lo16(zv.y)), y3 = gt[3] * (av[3] + skip * hi16(zv.y));
;             u32x2 o; o.x = pk2(y0, y1); o.y = pk2(y2, y3);
;             if (order == 0) *zp = o; else *(GAS u32x2*)(zt + (unsigned)tok) = o;
.LBB0_503:
	v_or_b32_e32 v27, v40, v38
	v_add_u32_e32 v26, v30, v39
	v_add_u32_e32 v27, 4, v27
	ds_read_b64 v[28:29], v26
	v_and_b32_e32 v27, s33, v27
	s_waitcnt vmcnt(14)
	v_and_b32_e32 v31, 0xffff0000, v23
	s_waitcnt vmcnt(12)
	v_lshlrev_b32_e32 v30, 16, v48
	v_cmp_ne_u32_e32 vcc, 0, v27
	v_and_b32_e32 v49, 16, v23
	v_and_b32_e32 v48, 0xffff0000, v22
	v_lshlrev_b32_e32 v51, 16, v23
	v_lshlrev_b32_e32 v23, 16, v22
	v_lshlrev_b32_e32 v22, 16, v47
	v_cndmask_b32_e32 v33, 0, v30, vcc
	v_mov_b32_e32 v50, v48
	v_mov_b32_e32 v30, v51
	v_pk_mov_b32 v[48:49], v[22:23], v[48:49] op_sel:[1,0]
	v_pk_mul_f32 v[52:53], v[18:19], v[30:31]
	v_pk_mul_f32 v[48:49], v[18:19], v[48:49]
	v_pk_fma_f32 v[52:53], v[16:17], v[50:51], v[52:53]
	v_mov_b32_e32 v32, v31
	v_pk_fma_f32 v[22:23], v[16:17], v[22:23], v[48:49]
	v_pk_fma_f32 v[30:31], v[0:1], v[32:33], v[52:53]
	s_waitcnt lgkmcnt(0)
	v_lshlrev_b32_e32 v32, 16, v28
	v_and_b32_e32 v33, 0xffff0000, v28
	v_pk_fma_f32 v[22:23], v[0:1], v[50:51], v[22:23]
	v_lshlrev_b32_e32 v28, 16, v29
	v_and_b32_e32 v29, 0xffff0000, v29
	v_pk_add_f32 v[30:31], v[2:3], v[30:31]
	v_pk_fma_f32 v[32:33], v[4:5], v[32:33], v[68:69]
	v_pk_add_f32 v[22:23], v[2:3], v[22:23]
	v_pk_fma_f32 v[28:29], v[4:5], v[28:29], v[70:71]
	v_pk_mul_f32 v[22:23], v[22:23], v[32:33]
	v_pk_mul_f32 v[28:29], v[30:31], v[28:29]
	v_cvt_pk_bf16_f32 v22, v22, v23
	v_cvt_pk_bf16_f32 v23, v28, v29
	s_and_b64 vcc, exec, s[6:7]
	s_mov_b64 s[0:1], -1
	s_cbranch_vccnz .LBB0_505
	v_add_u32_e32 v80, v40, v25
	v_lshl_add_u64 v[28:29], v[80:81], 1, s[14:15]
	s_mov_b64 s[0:1], 0
	v_mov_b32_e32 v162, v22
	v_mov_b32_e32 v163, v23
	v_bfe_u32 v166, v225, 4, 1
	v_mul_u32_u24_e32 v166, 24, v166
	v_mov_b32_e32 v167, 0
	v_lshl_add_u64 v[164:165], v[166:167], 0, v[28:29]
	s_nop 1
	v_permlane16_swap_b32_e32 v160, v162
	v_permlane16_swap_b32_e32 v161, v163
	global_store_dwordx4 v[164:165], v[160:163], off offset:64

; #define LAS __attribute__((address_space(3)))
; #define GAS __attribute__((address_space(1)))
; __device__ __forceinline__ unsigned pk2(float lo, float hi) { const f32x2_t f = {lo, hi}; const bf16x2_t b = __builtin_convertvector(f, bf16x2_t); return __builtin_bit_cast(unsigned, b); }
; __device__ __forceinline__ float lo16(unsigned v) { return __uint_as_float(v << 16); }
; __device__ __forceinline__ float hi16(unsigned v) { return __uint_as_float(v & 0xffff0000u); }
; __device__ __forceinline__ void conv_item(const Params& P, int slice, int item, LAS unsigned char* lds) {
;     ...
;         for (int hh = 0; hh < 2; ++hh) {
;           const int n = 32 * (2 * wn + nt) + 16 * hh + l16, bk = n >> nbsh, bs = n & (nb - 1), Bo = bs * nblk + bk;
; #pragma unroll
;           for (int mt = 0; mt < 4; ++mt) {
;             const int s0 = 64 * wm + 16 * mt + 4 * kc, tok = Bo * 128 + s0;
;             LAS u32x2* zp = (LAS u32x2*)(Zs + Bo * ZBLK + bs * 32 + 2 * s0);
;             const u32x2 zv = *zp; const f32x4 gt = sc4_apply(gr[hh][mt], tok, L, w0, w1, w2, bb);
;             const f32x4 av = acc[mt][2 * nt + hh];
;             const float y0 = gt[0] * (av[0] + skip * lo16(zv.x)), y1 = gt[1] * (av[1] + skip * hi16(zv.x));
;             const float y2 = gt[2] * (av[2] + skip * lo16(zv.y)), y3 = gt[3] * (av[3] + skip * hi16(zv.y));
;             u32x2 o; o.x = pk2(y0, y1); o.y = pk2(y2, y3);
;             if (order == 0) *zp = o; else *(GAS u32x2*)(zt + (unsigned)tok) = o;
.LBB0_507:
	v_mad_u64_u32 v[22:23], s[0:1], v44, s85, v[24:25]
	v_and_b32_e32 v28, s33, v14
	v_add_u32_e32 v23, v22, v59
	v_cmp_ne_u32_e32 vcc, 0, v28
	v_add_u32_e32 v28, 4, v14
	ds_read_b64 v[26:27], v23
	s_waitcnt vmcnt(11)
	v_lshlrev_b32_e32 v30, 16, v45
	v_and_b32_e32 v28, s33, v28
	s_waitcnt vmcnt(5)
	v_lshlrev_b32_e32 v24, 16, v20
	v_and_b32_e32 v29, 0xffff0000, v21
	v_cndmask_b32_e32 v31, 0, v30, vcc
	v_lshlrev_b32_e32 v30, 16, v46
	v_cmp_ne_u32_e32 vcc, 0, v28
	v_and_b32_e32 v20, 0xffff0000, v20
	v_lshlrev_b32_e32 v21, 16, v21
	v_cndmask_b32_e32 v33, 0, v30, vcc
	v_mov_b32_e32 v28, v21
	v_mov_b32_e32 v30, v20
	v_pk_mul_f32 v[44:45], v[18:19], v[28:29]
	v_pk_mul_f32 v[30:31], v[6:7], v[30:31]
	v_pk_fma_f32 v[44:45], v[16:17], v[20:21], v[44:45]
	v_mov_b32_e32 v32, v29
	v_pk_fma_f32 v[6:7], v[6:7], v[24:25], v[30:31] op_sel:[0,0,1] op_sel_hi:[1,0,0]
	v_pk_fma_f32 v[28:29], v[0:1], v[32:33], v[44:45]
	s_waitcnt lgkmcnt(0)
	v_lshlrev_b32_e32 v32, 16, v26
	v_and_b32_e32 v33, 0xffff0000, v26
	v_pk_fma_f32 v[6:7], v[0:1], v[20:21], v[6:7]
	v_lshlrev_b32_e32 v20, 16, v27
	v_and_b32_e32 v21, 0xffff0000, v27
	v_pk_add_f32 v[28:29], v[2:3], v[28:29]
	v_pk_fma_f32 v[32:33], v[4:5], v[32:33], v[112:113]
	v_pk_add_f32 v[6:7], v[2:3], v[6:7]
	v_pk_fma_f32 v[20:21], v[4:5], v[20:21], v[114:115]
	v_pk_mul_f32 v[6:7], v[6:7], v[32:33]
	v_pk_mul_f32 v[20:21], v[28:29], v[20:21]
	v_cvt_pk_bf16_f32 v6, v6, v7
	v_cvt_pk_bf16_f32 v7, v20, v21
	s_and_b64 vcc, exec, s[6:7]
	s_mov_b64 s[0:1], -1
	s_cbranch_vccnz .LBB0_509
	v_lshl_add_u64 v[14:15], v[14:15], 1, s[14:15]
	s_mov_b64 s[0:1], 0
	v_mov_b32_e32 v160, v6
	v_mov_b32_e32 v161, v7

; #define LAS __attribute__((address_space(3)))
; #define GAS __attribute__((address_space(1)))
; __device__ __forceinline__ unsigned pk2(float lo, float hi) { const f32x2_t f = {lo, hi}; const bf16x2_t b = __builtin_convertvector(f, bf16x2_t); return __builtin_bit_cast(unsigned, b); }
; __device__ __forceinline__ float lo16(unsigned v) { return __uint_as_float(v << 16); }
; __device__ __forceinline__ float hi16(unsigned v) { return __uint_as_float(v & 0xffff0000u); }
; __device__ __forceinline__ void conv_item(const Params& P, int slice, int item, LAS unsigned char* lds) {
;     ...
;         for (int hh = 0; hh < 2; ++hh) {
;           const int n = 32 * (2 * wn + nt) + 16 * hh + l16, bk = n >> nbsh, bs = n & (nb - 1), Bo = bs * nblk + bk;
; #pragma unroll
;           for (int mt = 0; mt < 4; ++mt) {
;             const int s0 = 64 * wm + 16 * mt + 4 * kc, tok = Bo * 128 + s0;
;             LAS u32x2* zp = (LAS u32x2*)(Zs + Bo * ZBLK + bs * 32 + 2 * s0);
;             const u32x2 zv = *zp; const f32x4 gt = sc4_apply(gr[hh][mt], tok, L, w0, w1, w2, bb);
;             const f32x4 av = acc[mt][2 * nt + hh];
;             const float y0 = gt[0] * (av[0] + skip * lo16(zv.x)), y1 = gt[1] * (av[1] + skip * hi16(zv.x));
;             const float y2 = gt[2] * (av[2] + skip * lo16(zv.y)), y3 = gt[3] * (av[3] + skip * hi16(zv.y));
;             u32x2 o; o.x = pk2(y0, y1); o.y = pk2(y2, y3);
;             if (order == 0) *zp = o; else *(GAS u32x2*)(zt + (unsigned)tok) = o;
.LBB0_511:
	v_or_b32_e32 v15, v34, v60
	v_add_u32_e32 v14, v22, v61
	v_add_u32_e32 v15, 4, v15
	ds_read_b64 v[6:7], v14
	v_and_b32_e32 v15, s33, v15
	s_waitcnt vmcnt(4)
	v_and_b32_e32 v21, 0xffff0000, v13
	s_waitcnt vmcnt(3)
	v_lshlrev_b32_e32 v20, 16, v43
	v_cmp_ne_u32_e32 vcc, 0, v15
	v_and_b32_e32 v29, 16, v13
	v_and_b32_e32 v28, 0xffff0000, v12
	v_lshlrev_b32_e32 v31, 16, v13
	v_lshlrev_b32_e32 v13, 16, v12
	v_lshlrev_b32_e32 v12, 16, v42
	v_cndmask_b32_e32 v27, 0, v20, vcc
	v_mov_b32_e32 v30, v28
	v_mov_b32_e32 v20, v31
	v_pk_mov_b32 v[28:29], v[12:13], v[28:29] op_sel:[1,0]
	v_pk_mul_f32 v[32:33], v[18:19], v[20:21]
	v_pk_mul_f32 v[28:29], v[18:19], v[28:29]
	v_pk_fma_f32 v[32:33], v[16:17], v[30:31], v[32:33]
	v_mov_b32_e32 v26, v21
	v_pk_fma_f32 v[12:13], v[16:17], v[12:13], v[28:29]
	v_pk_fma_f32 v[20:21], v[0:1], v[26:27], v[32:33]
	s_waitcnt lgkmcnt(0)
	v_lshlrev_b32_e32 v26, 16, v6
	v_and_b32_e32 v27, 0xffff0000, v6
	v_pk_fma_f32 v[12:13], v[0:1], v[30:31], v[12:13]
	v_lshlrev_b32_e32 v6, 16, v7
	v_and_b32_e32 v7, 0xffff0000, v7
	v_pk_add_f32 v[20:21], v[2:3], v[20:21]
	v_pk_fma_f32 v[26:27], v[4:5], v[26:27], v[108:109]
	v_pk_add_f32 v[12:13], v[2:3], v[12:13]
	v_pk_fma_f32 v[6:7], v[4:5], v[6:7], v[110:111]
	v_pk_mul_f32 v[12:13], v[12:13], v[26:27]
	v_pk_mul_f32 v[20:21], v[20:21], v[6:7]
	v_cvt_pk_bf16_f32 v6, v12, v13
	v_cvt_pk_bf16_f32 v7, v20, v21
	s_and_b64 vcc, exec, s[6:7]
	s_mov_b64 s[0:1], -1
	s_cbranch_vccnz .LBB0_513
	v_add_u32_e32 v80, v34, v25
	v_lshl_add_u64 v[12:13], v[80:81], 1, s[14:15]
	s_mov_b64 s[0:1], 0
	v_mov_b32_e32 v162, v6
	v_mov_b32_e32 v163, v7
	v_bfe_u32 v166, v225, 4, 1
	v_mul_u32_u24_e32 v166, 24, v166
	v_mov_b32_e32 v167, 0
	v_lshl_add_u64 v[164:165], v[166:167], 0, v[12:13]
	s_nop 1
	v_permlane16_swap_b32_e32 v160, v162
	v_permlane16_swap_b32_e32 v161, v163
	global_store_dwordx4 v[164:165], v[160:163], off

; #define LAS __attribute__((address_space(3)))
; #define GAS __attribute__((address_space(1)))
; __device__ __forceinline__ unsigned pk2(float lo, float hi) { const f32x2_t f = {lo, hi}; const bf16x2_t b = __builtin_convertvector(f, bf16x2_t); return __builtin_bit_cast(unsigned, b); }
; __device__ __forceinline__ float lo16(unsigned v) { return __uint_as_float(v << 16); }
; __device__ __forceinline__ float hi16(unsigned v) { return __uint_as_float(v & 0xffff0000u); }
; __device__ __forceinline__ void conv_item(const Params& P, int slice, int item, LAS unsigned char* lds) {
;     ...
;         for (int hh = 0; hh < 2; ++hh) {
;           const int n = 32 * (2 * wn + nt) + 16 * hh + l16, bk = n >> nbsh, bs = n & (nb - 1), Bo = bs * nblk + bk;
; #pragma unroll
;           for (int mt = 0; mt < 4; ++mt) {
;             const int s0 = 64 * wm + 16 * mt + 4 * kc, tok = Bo * 128 + s0;
;             LAS u32x2* zp = (LAS u32x2*)(Zs + Bo * ZBLK + bs * 32 + 2 * s0);
;             const u32x2 zv = *zp; const f32x4 gt = sc4_apply(gr[hh][mt], tok, L, w0, w1, w2, bb);
;             const f32x4 av = acc[mt][2 * nt + hh];
;             const float y0 = gt[0] * (av[0] + skip * lo16(zv.x)), y1 = gt[1] * (av[1] + skip * hi16(zv.x));
;             const float y2 = gt[2] * (av[2] + skip * lo16(zv.y)), y3 = gt[3] * (av[3] + skip * hi16(zv.y));
;             u32x2 o; o.x = pk2(y0, y1); o.y = pk2(y2, y3);
;             if (order == 0) *zp = o; else *(GAS u32x2*)(zt + (unsigned)tok) = o;
.LBB0_515:
	v_add_u32_e32 v12, v22, v56
	ds_read_b64 v[6:7], v12
	s_waitcnt vmcnt(1)
	v_and_b32_e32 v15, 0xffff0000, v11
	v_and_b32_e32 v27, 16, v11
	v_and_b32_e32 v26, 0xffff0000, v10
	v_lshlrev_b32_e32 v29, 16, v11
	v_lshlrev_b32_e32 v11, 16, v10
	v_lshlrev_b32_e32 v10, 16, v37
	v_mov_b32_e32 v28, v26
	v_mov_b32_e32 v14, v29
	v_pk_mov_b32 v[26:27], v[10:11], v[26:27] op_sel:[1,0]
	v_mov_b32_e32 v20, v15
	v_pk_mul_f32 v[14:15], v[18:19], v[14:15]
	v_pk_mul_f32 v[26:27], v[18:19], v[26:27]
	v_lshlrev_b32_e32 v21, 16, v41
	v_pk_fma_f32 v[14:15], v[16:17], v[28:29], v[14:15]
	v_pk_fma_f32 v[10:11], v[16:17], v[10:11], v[26:27]
	v_pk_fma_f32 v[14:15], v[0:1], v[20:21], v[14:15]
	s_waitcnt lgkmcnt(0)
	v_lshlrev_b32_e32 v20, 16, v6
	v_and_b32_e32 v21, 0xffff0000, v6
	v_pk_fma_f32 v[10:11], v[0:1], v[28:29], v[10:11]
	v_lshlrev_b32_e32 v6, 16, v7
	v_and_b32_e32 v7, 0xffff0000, v7
	v_pk_add_f32 v[14:15], v[2:3], v[14:15]
	v_pk_fma_f32 v[20:21], v[4:5], v[20:21], v[104:105]
	v_pk_add_f32 v[10:11], v[2:3], v[10:11]
	v_pk_fma_f32 v[6:7], v[4:5], v[6:7], v[106:107]
	v_pk_mul_f32 v[10:11], v[10:11], v[20:21]
	v_pk_mul_f32 v[14:15], v[14:15], v[6:7]
	v_cvt_pk_bf16_f32 v6, v10, v11
	v_cvt_pk_bf16_f32 v7, v14, v15
	s_and_b64 vcc, exec, s[6:7]
	s_mov_b64 s[0:1], -1
	s_cbranch_vccnz .LBB0_517
	v_add_u32_e32 v80, v34, v25
	v_lshl_add_u64 v[10:11], v[80:81], 1, s[14:15]
	s_mov_b64 s[0:1], 0
	v_mov_b32_e32 v160, v6
	v_mov_b32_e32 v161, v7

; #define LAS __attribute__((address_space(3)))
; #define GAS __attribute__((address_space(1)))
; __device__ __forceinline__ unsigned pk2(float lo, float hi) { const f32x2_t f = {lo, hi}; const bf16x2_t b = __builtin_convertvector(f, bf16x2_t); return __builtin_bit_cast(unsigned, b); }
; __device__ __forceinline__ float lo16(unsigned v) { return __uint_as_float(v << 16); }
; __device__ __forceinline__ float hi16(unsigned v) { return __uint_as_float(v & 0xffff0000u); }
; __device__ __forceinline__ void conv_item(const Params& P, int slice, int item, LAS unsigned char* lds) {
;     ...
;         for (int hh = 0; hh < 2; ++hh) {
;           const int n = 32 * (2 * wn + nt) + 16 * hh + l16, bk = n >> nbsh, bs = n & (nb - 1), Bo = bs * nblk + bk;
; #pragma unroll
;           for (int mt = 0; mt < 4; ++mt) {
;             const int s0 = 64 * wm + 16 * mt + 4 * kc, tok = Bo * 128 + s0;
;             LAS u32x2* zp = (LAS u32x2*)(Zs + Bo * ZBLK + bs * 32 + 2 * s0);
;             const u32x2 zv = *zp; const f32x4 gt = sc4_apply(gr[hh][mt], tok, L, w0, w1, w2, bb);
;             const f32x4 av = acc[mt][2 * nt + hh];
;             const float y0 = gt[0] * (av[0] + skip * lo16(zv.x)), y1 = gt[1] * (av[1] + skip * hi16(zv.x));
;             const float y2 = gt[2] * (av[2] + skip * lo16(zv.y)), y3 = gt[3] * (av[3] + skip * hi16(zv.y));
;             u32x2 o; o.x = pk2(y0, y1); o.y = pk2(y2, y3);
;             if (order == 0) *zp = o; else *(GAS u32x2*)(zt + (unsigned)tok) = o;
.LBB0_519:
	v_or_b32_e32 v7, v34, v38
	v_add_u32_e32 v7, 4, v7
	v_add_u32_e32 v6, v22, v39
	v_and_b32_e32 v7, s33, v7
	ds_read_b64 v[10:11], v6
	s_waitcnt vmcnt(0)
	v_and_b32_e32 v13, 0xffff0000, v9
	v_lshlrev_b32_e32 v12, 16, v36
	v_cmp_ne_u32_e32 vcc, 0, v7
	v_and_b32_e32 v21, 16, v9
	v_and_b32_e32 v20, 0xffff0000, v8
	v_lshlrev_b32_e32 v23, 16, v9
	v_lshlrev_b32_e32 v9, 16, v8
	v_lshlrev_b32_e32 v8, 16, v35
	v_cndmask_b32_e32 v15, 0, v12, vcc
	v_mov_b32_e32 v22, v20
	v_mov_b32_e32 v12, v23
	v_pk_mov_b32 v[20:21], v[8:9], v[20:21] op_sel:[1,0]
	v_pk_mul_f32 v[26:27], v[18:19], v[12:13]
	v_pk_mul_f32 v[18:19], v[18:19], v[20:21]
	v_pk_fma_f32 v[26:27], v[16:17], v[22:23], v[26:27]
	v_mov_b32_e32 v14, v13
	v_pk_fma_f32 v[8:9], v[16:17], v[8:9], v[18:19]
	v_pk_fma_f32 v[12:13], v[0:1], v[14:15], v[26:27]
	v_pk_fma_f32 v[0:1], v[0:1], v[22:23], v[8:9]
	v_pk_add_f32 v[12:13], v[2:3], v[12:13]
	s_waitcnt lgkmcnt(0)
	v_lshlrev_b32_e32 v14, 16, v10
	v_and_b32_e32 v15, 0xffff0000, v10
	v_pk_add_f32 v[0:1], v[2:3], v[0:1]
	v_lshlrev_b32_e32 v2, 16, v11
	v_and_b32_e32 v3, 0xffff0000, v11
	v_pk_fma_f32 v[14:15], v[4:5], v[14:15], v[100:101]
	v_pk_fma_f32 v[2:3], v[4:5], v[2:3], v[102:103]
	v_pk_mul_f32 v[0:1], v[0:1], v[14:15]
	v_pk_mul_f32 v[2:3], v[12:13], v[2:3]
	v_cvt_pk_bf16_f32 v0, v0, v1
	v_cvt_pk_bf16_f32 v1, v2, v3
	s_and_b64 vcc, exec, s[6:7]
	s_mov_b64 s[0:1], -1
	s_cbranch_vccnz .LBB0_521
	v_add_u32_e32 v80, v34, v25
	v_lshl_add_u64 v[2:3], v[80:81], 1, s[14:15]
	s_mov_b64 s[0:1], 0
	v_mov_b32_e32 v162, v0
	v_mov_b32_e32 v163, v1
	v_bfe_u32 v166, v225, 4, 1
	v_mul_u32_u24_e32 v166, 24, v166
	v_mov_b32_e32 v167, 0
	v_lshl_add_u64 v[164:165], v[166:167], 0, v[2:3]
	s_nop 1
	v_permlane16_swap_b32_e32 v160, v162
	v_permlane16_swap_b32_e32 v161, v163
	global_store_dwordx4 v[164:165], v[160:163], off offset:64
